# v7 plus 32-bit row*pitch address arithmetic in the sample attention chunk loop (6 sites: sign fix-up mad_u64 and 64-bit shift removed; rows are non-negative and row*pitch fits 24 bits)
# speedup vs baseline: 1.0506x; 1.0090x over previous
.LBB0_1326:
	v_subrev_u32_e32 v32, 28, v182
	v_min_i32_e32 v32, s53, v32
	v_mul_lo_u32 v32, v32, v177
	v_add_u32_e32 v32, v32, v178
	v_add_u32_e32 v33, -8, v32
	v_cmp_lt_i32_e32 vcc, v32, v180
	v_add_u32_e32 v211, v127, v129
	ds_read_b128 v[216:219], v211 offset:64
	v_cndmask_b32_e32 v32, v33, v32, vcc
	v_mul_u32_u24_e32 v32, v32, v141
	v_mov_b32_e32 v33, 0
	v_or_b32_e32 v32, v32, v130
	v_cndmask_b32_e32 v35, v145, v149, vcc
	v_cndmask_b32_e32 v34, v144, v148, vcc
	v_lshlrev_b32_e32 v32, 2, v32
	v_lshl_add_u64 v[34:35], v[34:35], 0, v[32:33]
	global_load_dwordx4 v[112:115], v[34:35], off
	v_cndmask_b32_e32 v35, v147, v151, vcc
	v_cndmask_b32_e32 v34, v146, v150, vcc
	v_lshl_add_u64 v[32:33], v[34:35], 0, v[32:33]
	global_load_dwordx4 v[116:119], v[32:33], off
	v_subrev_u32_e32 v32, 24, v182
	v_min_i32_e32 v32, s53, v32
	v_mul_lo_u32 v32, v32, v177
	v_add_u32_e32 v32, v32, v178
	v_add_u32_e32 v33, -8, v32
	v_cmp_lt_i32_e32 vcc, v32, v180
	v_min_i32_e32 v120, s53, v182
	v_mul_lo_u32 v120, v120, v177
	v_cndmask_b32_e32 v32, v33, v32, vcc
	v_mul_u32_u24_e32 v32, v32, v141
	v_mov_b32_e32 v33, 0
	v_or_b32_e32 v32, v32, v130
	v_cndmask_b32_e32 v35, v145, v149, vcc
	v_cndmask_b32_e32 v34, v144, v148, vcc
	v_lshlrev_b32_e32 v32, 2, v32
	v_lshl_add_u64 v[34:35], v[34:35], 0, v[32:33]
	global_load_dwordx4 v[104:107], v[34:35], off
	v_cndmask_b32_e32 v35, v147, v151, vcc
	v_cndmask_b32_e32 v34, v146, v150, vcc
	v_lshl_add_u64 v[32:33], v[34:35], 0, v[32:33]
	global_load_dwordx4 v[108:111], v[32:33], off
	v_subrev_u32_e32 v32, 20, v182
	v_min_i32_e32 v32, s53, v32
	v_mul_lo_u32 v32, v32, v177
	v_add_u32_e32 v32, v32, v178
	v_add_u32_e32 v33, -8, v32
	v_cmp_lt_i32_e32 vcc, v32, v180
	v_add_u32_e32 v120, v120, v178
	v_add_u32_e32 v209, -8, v120
	v_cndmask_b32_e32 v32, v33, v32, vcc
	v_mul_u32_u24_e32 v32, v32, v141
	v_mov_b32_e32 v33, 0
	v_or_b32_e32 v32, v32, v130
	v_cndmask_b32_e32 v35, v145, v149, vcc
	v_cndmask_b32_e32 v34, v144, v148, vcc
	v_lshlrev_b32_e32 v32, 2, v32
	v_lshl_add_u64 v[34:35], v[34:35], 0, v[32:33]
	global_load_dwordx4 v[96:99], v[34:35], off
	v_cndmask_b32_e32 v35, v147, v151, vcc
	v_cndmask_b32_e32 v34, v146, v150, vcc
	v_lshl_add_u64 v[32:33], v[34:35], 0, v[32:33]
	global_load_dwordx4 v[100:103], v[32:33], off
	v_add_u32_e32 v32, -16, v182
	v_min_i32_e32 v32, s53, v32
	v_mul_lo_u32 v32, v32, v177
	v_add_u32_e32 v32, v32, v178
	v_add_u32_e32 v33, -8, v32
	v_cmp_lt_i32_e32 vcc, v32, v180
	v_add_u32_e32 v184, v184, v186
	v_add_u32_e32 v201, v201, v185
	v_cndmask_b32_e32 v32, v33, v32, vcc
	v_mul_u32_u24_e32 v32, v32, v141
	v_mov_b32_e32 v33, 0
	v_or_b32_e32 v32, v32, v130
	v_cndmask_b32_e32 v35, v145, v149, vcc
	v_cndmask_b32_e32 v34, v144, v148, vcc
	v_lshlrev_b32_e32 v32, 2, v32
	v_lshl_add_u64 v[34:35], v[34:35], 0, v[32:33]
	global_load_dwordx4 v[88:91], v[34:35], off
	v_cndmask_b32_e32 v35, v147, v151, vcc
	v_cndmask_b32_e32 v34, v146, v150, vcc
	v_lshl_add_u64 v[32:33], v[34:35], 0, v[32:33]
	global_load_dwordx4 v[92:95], v[32:33], off
	v_add_u32_e32 v32, -12, v182
	v_min_i32_e32 v32, s53, v32
	v_mul_lo_u32 v32, v32, v177
	v_add_u32_e32 v32, v32, v178
	v_add_u32_e32 v33, -8, v32
	v_cmp_lt_i32_e32 vcc, v32, v180
	ds_read_b128 v[212:215], v211 offset:32
	v_add_u32_e32 v188, v188, v186
	v_cndmask_b32_e32 v32, v33, v32, vcc
	v_mul_u32_u24_e32 v32, v32, v141
	v_mov_b32_e32 v33, 0
	v_or_b32_e32 v32, v32, v130
	v_cndmask_b32_e32 v35, v145, v149, vcc
	v_cndmask_b32_e32 v34, v144, v148, vcc
	v_lshlrev_b32_e32 v32, 2, v32
	v_lshl_add_u64 v[34:35], v[34:35], 0, v[32:33]
	global_load_dwordx4 v[80:83], v[34:35], off
	v_cndmask_b32_e32 v35, v147, v151, vcc
	v_cndmask_b32_e32 v34, v146, v150, vcc
	v_lshl_add_u64 v[32:33], v[34:35], 0, v[32:33]
	global_load_dwordx4 v[84:87], v[32:33], off
	v_add_u32_e32 v32, -8, v182
	v_min_i32_e32 v32, s53, v32
	v_mul_lo_u32 v32, v32, v177
	v_add_u32_e32 v32, v32, v178
	v_add_u32_e32 v33, -8, v32
	v_cmp_lt_i32_e32 vcc, v32, v180
	v_add_u32_e32 v190, v190, v186
	v_add_u32_e32 v192, v192, v186
	v_cndmask_b32_e32 v32, v33, v32, vcc
	v_mul_u32_u24_e32 v32, v32, v141
	v_mov_b32_e32 v33, 0
	v_or_b32_e32 v32, v32, v130
	v_cndmask_b32_e32 v35, v145, v149, vcc
	v_cndmask_b32_e32 v34, v144, v148, vcc
	v_lshlrev_b32_e32 v32, 2, v32
	v_lshl_add_u64 v[34:35], v[34:35], 0, v[32:33]
	global_load_dwordx4 v[64:67], v[34:35], off
	v_cndmask_b32_e32 v35, v147, v151, vcc
	v_cndmask_b32_e32 v34, v146, v150, vcc
	v_lshl_add_u64 v[32:33], v[34:35], 0, v[32:33]
	global_load_dwordx4 v[68:71], v[32:33], off
	v_add_u32_e32 v32, -4, v182
	v_min_i32_e32 v32, s53, v32
	v_mul_lo_u32 v32, v32, v177
	v_add_u32_e32 v32, v32, v178
	v_add_u32_e32 v33, -8, v32
	v_cmp_lt_i32_e32 vcc, v32, v180
	v_add_u32_e32 v182, 32, v182
	v_add_u32_e32 v194, v194, v186
	v_cndmask_b32_e32 v32, v33, v32, vcc
	v_ashrrev_i32_e32 v35, 31, v32
	v_mad_u64_u32 v[32:33], s[16:17], v32, v141, 0
	v_mov_b32_e32 v34, v33
	v_mad_u64_u32 v[34:35], s[16:17], v35, v141, v[34:35]
	v_or_b32_e32 v36, v32, v130
	v_mov_b32_e32 v37, v34
	ds_read_b128 v[32:35], v211
	v_cndmask_b32_e32 v39, v145, v149, vcc
	v_cndmask_b32_e32 v38, v144, v148, vcc
	v_lshlrev_b64 v[76:77], 2, v[36:37]
	v_lshl_add_u64 v[36:37], v[38:39], 0, v[76:77]
	global_load_dwordx4 v[72:75], v[36:37], off
	s_waitcnt lgkmcnt(0)
	v_mfma_f32_32x32x16_bf16 v[32:47], v[32:35], v[56:59], 0
	v_cndmask_b32_e32 v79, v147, v151, vcc
	v_cndmask_b32_e32 v78, v146, v150, vcc
	v_cmp_lt_i32_e32 vcc, v120, v180
	v_lshl_add_u64 v[76:77], v[78:79], 0, v[76:77]
	global_load_dwordx4 v[76:79], v[76:77], off
	v_cndmask_b32_e32 v120, v209, v120, vcc
	v_mad_u64_u32 v[220:221], s[16:17], v120, v141, 0
	v_mfma_f32_32x32x16_bf16 v[32:47], v[212:215], v[60:63], v[32:47]
	ds_read_b128 v[212:215], v211 offset:96
	v_ashrrev_i32_e32 v209, 31, v120
	v_mov_b32_e32 v120, v221
	v_add_u32_e32 v196, v196, v186
	v_add_u32_e32 v198, v198, v186
	v_add_u32_e32 v200, v200, v186
	v_mfma_f32_32x32x16_bf16 v[32:47], v[216:219], v[52:55], v[32:47]
	v_mad_u64_u32 v[216:217], s[16:17], v209, v141, v[120:121]
	v_add_u32_e32 v120, s33, v181
	v_cmp_le_u32_e64 s[16:17], v120, v135
	v_or_b32_e32 v218, v220, v130
	v_mov_b32_e32 v219, v216
	v_cndmask_b32_e32 v217, v145, v149, vcc
	s_waitcnt lgkmcnt(0)
	v_mfma_f32_32x32x16_bf16 v[32:47], v[212:215], v[48:51], v[32:47]
	v_cndmask_b32_e32 v216, v144, v148, vcc
	v_lshlrev_b64 v[218:219], 2, v[218:219]
	s_sub_i32 s33, s33, 32
	s_nop 8
	v_cndmask_b32_e64 v210, v173, v32, s[16:17]
	v_add_u32_e32 v32, -1, v120
	v_cmp_le_u32_e64 s[16:17], v32, v135
	s_nop 1
	v_cndmask_b32_e64 v212, v173, v33, s[16:17]
	v_add_u32_e32 v33, -2, v120
	v_cmp_le_u32_e64 s[16:17], v33, v135
	v_add_u32_e32 v33, -3, v120
	v_max3_f32 v32, v210, s90, v212
	v_cndmask_b32_e64 v213, v173, v34, s[16:17]
	v_cmp_le_u32_e64 s[16:17], v33, v135
	v_add_u32_e32 v33, -8, v120
	s_nop 0
	v_cndmask_b32_e64 v214, v173, v35, s[16:17]
	v_cmp_le_u32_e64 s[16:17], v33, v135
	v_add_u32_e32 v33, -9, v120
	v_max3_f32 v32, v32, v213, v214
	v_cndmask_b32_e64 v215, v173, v36, s[16:17]
	v_cmp_le_u32_e64 s[16:17], v33, v135
	v_add_u32_e32 v33, -10, v120
	v_cndmask_b32_e32 v36, v146, v150, vcc
	v_cndmask_b32_e64 v220, v173, v37, s[16:17]
	v_cmp_le_u32_e64 s[16:17], v33, v135
	v_add_u32_e32 v33, -11, v120
	v_max3_f32 v32, v32, v215, v220
	v_cndmask_b32_e64 v221, v173, v38, s[16:17]
	v_cmp_le_u32_e64 s[16:17], v33, v135
	v_add_u32_e32 v33, -16, v120
	v_cndmask_b32_e32 v37, v147, v151, vcc
	v_cndmask_b32_e64 v222, v173, v39, s[16:17]
	v_cmp_le_u32_e64 s[16:17], v33, v135
	v_subrev_u32_e32 v33, 17, v120
	v_max3_f32 v32, v32, v221, v222
	v_cndmask_b32_e64 v40, v173, v40, s[16:17]
	v_cmp_le_u32_e64 s[16:17], v33, v135
	v_subrev_u32_e32 v33, 18, v120
	v_lshl_add_u64 v[36:37], v[36:37], 0, v[218:219]
	v_cndmask_b32_e64 v41, v173, v41, s[16:17]
	v_cmp_le_u32_e64 s[16:17], v33, v135
	v_subrev_u32_e32 v33, 19, v120
	v_max3_f32 v32, v32, v40, v41
	v_cndmask_b32_e64 v42, v173, v42, s[16:17]
	v_cmp_le_u32_e64 s[16:17], v33, v135
	v_subrev_u32_e32 v33, 24, v120
	s_nop 0
	v_cndmask_b32_e64 v43, v173, v43, s[16:17]
	v_cmp_le_u32_e64 s[16:17], v33, v135
	v_subrev_u32_e32 v33, 25, v120
	v_max3_f32 v32, v32, v42, v43
	v_cndmask_b32_e64 v44, v173, v44, s[16:17]
	v_cmp_le_u32_e64 s[16:17], v33, v135
	v_subrev_u32_e32 v33, 26, v120
	s_nop 0
	v_cndmask_b32_e64 v45, v173, v45, s[16:17]
	v_cmp_le_u32_e64 s[16:17], v33, v135
	v_subrev_u32_e32 v33, 27, v120
	v_max3_f32 v32, v32, v44, v45
	v_cndmask_b32_e64 v46, v173, v46, s[16:17]
	v_cmp_le_u32_e64 s[16:17], v33, v135
	s_nop 1
	v_cndmask_b32_e64 v47, v173, v47, s[16:17]
	v_max3_f32 v38, v32, v46, v47
	ds_bpermute_b32 v39, v143, v38
	v_lshl_add_u64 v[32:33], v[216:217], 0, v[218:219]
	global_load_dwordx4 v[32:35], v[32:33], off
	s_add_i32 s16, s18, s33
	s_cmp_lg_u32 s16, 0
	s_waitcnt lgkmcnt(0)
	v_max3_f32 v209, v208, v38, v39
	v_sub_f32_e32 v38, v210, v209
	v_exp_f32_e32 v210, v38
	global_load_dwordx4 v[36:39], v[36:37], off
	v_sub_f32_e32 v212, v212, v209
	v_exp_f32_e32 v212, v212
	v_sub_f32_e32 v213, v213, v209
	v_exp_f32_e32 v213, v213
	v_sub_f32_e32 v214, v214, v209
	v_exp_f32_e32 v214, v214
	v_sub_f32_e32 v215, v215, v209
	v_sub_f32_e32 v120, v208, v209
	v_add_f32_e32 v208, 0, v210
	v_exp_f32_e32 v215, v215
	v_sub_f32_e32 v216, v220, v209
	v_add_f32_e32 v208, v212, v208
	v_exp_f32_e32 v216, v216
	v_sub_f32_e32 v217, v221, v209
	v_add_f32_e32 v208, v213, v208
	v_exp_f32_e32 v217, v217
	v_sub_f32_e32 v218, v222, v209
	v_add_f32_e32 v208, v214, v208
	v_exp_f32_e32 v218, v218
	v_sub_f32_e32 v40, v40, v209
	v_add_f32_e32 v208, v215, v208
	v_exp_f32_e32 v220, v40
	v_sub_f32_e32 v41, v41, v209
	v_add_f32_e32 v40, v216, v208
	v_exp_f32_e32 v208, v41
	v_sub_f32_e32 v41, v42, v209
	v_add_f32_e32 v40, v217, v40
	v_exp_f32_e32 v221, v41
	v_sub_f32_e32 v41, v43, v209
	v_add_f32_e32 v40, v218, v40
	v_exp_f32_e32 v222, v41
	v_sub_f32_e32 v41, v44, v209
	v_add_f32_e32 v40, v220, v40
	v_exp_f32_e32 v223, v41
	v_sub_f32_e32 v41, v45, v209
	v_add_f32_e32 v40, v208, v40
	v_exp_f32_e32 v224, v41
	v_sub_f32_e32 v41, v46, v209
	v_add_f32_e32 v40, v221, v40
	v_exp_f32_e32 v225, v41
	v_sub_f32_e32 v41, v47, v209
	v_add_f32_e32 v40, v222, v40
	v_exp_f32_e32 v226, v41
	v_add_f32_e32 v40, v223, v40
	v_add_f32_e32 v40, v224, v40
	v_add_f32_e32 v40, v225, v40
	v_exp_f32_e32 v120, v120
	v_add_f32_e32 v227, v226, v40
	ds_read_b64_tr_b16 v[40:41], v175 offset:4608
	ds_read_b64_tr_b16 v[42:43], v175 offset:5760
	v_cvt_pk_bf16_f32 v44, v210, v212
	v_cvt_pk_bf16_f32 v45, v213, v214
	v_cvt_pk_bf16_f32 v46, v215, v216
	v_cvt_pk_bf16_f32 v47, v217, v218
	ds_read_b64_tr_b16 v[212:213], v175 offset:6912
	ds_read_b64_tr_b16 v[214:215], v175 offset:8064
	ds_read_b64_tr_b16 v[218:219], v175 offset:5824
	ds_read_b64_tr_b16 v[216:217], v175 offset:4672
	v_pk_mul_f32 v[14:15], v[14:15], v[120:121] op_sel_hi:[1,0]
	v_pk_mul_f32 v[12:13], v[12:13], v[120:121] op_sel_hi:[1,0]
	v_pk_mul_f32 v[10:11], v[10:11], v[120:121] op_sel_hi:[1,0]
	v_pk_mul_f32 v[8:9], v[8:9], v[120:121] op_sel_hi:[1,0]
	v_pk_mul_f32 v[6:7], v[6:7], v[120:121] op_sel_hi:[1,0]
	v_pk_mul_f32 v[4:5], v[4:5], v[120:121] op_sel_hi:[1,0]
	v_pk_mul_f32 v[2:3], v[2:3], v[120:121] op_sel_hi:[1,0]
	v_pk_mul_f32 v[0:1], v[0:1], v[120:121] op_sel_hi:[1,0]
	v_pk_mul_f32 v[30:31], v[30:31], v[120:121] op_sel_hi:[1,0]
	v_pk_mul_f32 v[28:29], v[28:29], v[120:121] op_sel_hi:[1,0]
	v_pk_mul_f32 v[26:27], v[26:27], v[120:121] op_sel_hi:[1,0]
	v_pk_mul_f32 v[24:25], v[24:25], v[120:121] op_sel_hi:[1,0]
	v_pk_mul_f32 v[22:23], v[22:23], v[120:121] op_sel_hi:[1,0]
	v_pk_mul_f32 v[20:21], v[20:21], v[120:121] op_sel_hi:[1,0]
	v_pk_mul_f32 v[18:19], v[18:19], v[120:121] op_sel_hi:[1,0]
	v_pk_mul_f32 v[16:17], v[16:17], v[120:121] op_sel_hi:[1,0]
	s_waitcnt lgkmcnt(4)
	v_mfma_f32_32x32x16_bf16 v[0:15], v[40:43], v[44:47], v[0:15]
	v_cvt_pk_bf16_f32 v40, v220, v208
	v_cvt_pk_bf16_f32 v41, v221, v222
	v_cvt_pk_bf16_f32 v42, v223, v224
	ds_read_b64_tr_b16 v[222:223], v175 offset:8128
	ds_read_b64_tr_b16 v[220:221], v175 offset:6976
	v_cvt_pk_bf16_f32 v43, v225, v226
	s_waitcnt lgkmcnt(2)
	v_mfma_f32_32x32x16_bf16 v[16:31], v[216:219], v[44:47], v[16:31]
	ds_bpermute_b32 v44, v143, v227
	s_waitcnt lgkmcnt(0)
	v_add_f32_e32 v210, v227, v44
	v_fmac_f32_e32 v210, v202, v120
	v_mfma_f32_32x32x16_bf16 v[0:15], v[212:215], v[40:43], v[0:15]
	v_mfma_f32_32x32x16_bf16 v[16:31], v[220:223], v[40:43], v[16:31]
	s_cbranch_scc0 .LBB0_1328
	v_mov_b32_e32 v208, v209
	v_mov_b32_e32 v202, v210
	s_branch .LBB0_1284
